# XB1: prologue x->bf16 conversion hand-written with all 32 loads of a thread in flight at once (was 4 serial rounds)
# speedup vs baseline: 1.0238x; 1.0063x over previous
.LBB0_103:
	s_or_b64 exec, exec, s[0:1]
	v_readlane_b32 s12, v234, 2
	v_readlane_b32 s13, v234, 3
	s_add_u32 s16, s80, 0x1a00000
	s_addc_u32 s17, s81, 0
	v_lshlrev_b32_e32 v0, 5, v4
	v_lshlrev_b32_e32 v2, 4, v4
	s_nop 3
	global_load_dwordx4 v[20:23], v0, s[12:13]
	global_load_dwordx4 v[24:27], v0, s[12:13] offset:16
	s_add_u32 s12, s12, 0x400000
	s_addc_u32 s13, s13, 0
	global_load_dwordx4 v[28:31], v0, s[12:13]
	global_load_dwordx4 v[32:35], v0, s[12:13] offset:16
	s_add_u32 s12, s12, 0x400000
	s_addc_u32 s13, s13, 0
	global_load_dwordx4 v[36:39], v0, s[12:13]
	global_load_dwordx4 v[40:43], v0, s[12:13] offset:16
	s_add_u32 s12, s12, 0x400000
	s_addc_u32 s13, s13, 0
	global_load_dwordx4 v[44:47], v0, s[12:13]
	global_load_dwordx4 v[48:51], v0, s[12:13] offset:16
	s_add_u32 s12, s12, 0x400000
	s_addc_u32 s13, s13, 0
	global_load_dwordx4 v[52:55], v0, s[12:13]
	global_load_dwordx4 v[56:59], v0, s[12:13] offset:16
	s_add_u32 s12, s12, 0x400000
	s_addc_u32 s13, s13, 0
	global_load_dwordx4 v[60:63], v0, s[12:13]
	global_load_dwordx4 v[64:67], v0, s[12:13] offset:16
	s_add_u32 s12, s12, 0x400000
	s_addc_u32 s13, s13, 0
	global_load_dwordx4 v[68:71], v0, s[12:13]
	global_load_dwordx4 v[72:75], v0, s[12:13] offset:16
	s_add_u32 s12, s12, 0x400000
	s_addc_u32 s13, s13, 0
	global_load_dwordx4 v[76:79], v0, s[12:13]
	global_load_dwordx4 v[80:83], v0, s[12:13] offset:16
	s_add_u32 s12, s12, 0x400000
	s_addc_u32 s13, s13, 0
	global_load_dwordx4 v[84:87], v0, s[12:13]
	global_load_dwordx4 v[88:91], v0, s[12:13] offset:16
	s_add_u32 s12, s12, 0x400000
	s_addc_u32 s13, s13, 0
	global_load_dwordx4 v[92:95], v0, s[12:13]
	global_load_dwordx4 v[96:99], v0, s[12:13] offset:16
	s_add_u32 s12, s12, 0x400000
	s_addc_u32 s13, s13, 0
	global_load_dwordx4 v[100:103], v0, s[12:13]
	global_load_dwordx4 v[104:107], v0, s[12:13] offset:16
	s_add_u32 s12, s12, 0x400000
	s_addc_u32 s13, s13, 0
	global_load_dwordx4 v[108:111], v0, s[12:13]
	global_load_dwordx4 v[112:115], v0, s[12:13] offset:16
	s_add_u32 s12, s12, 0x400000
	s_addc_u32 s13, s13, 0
	global_load_dwordx4 v[116:119], v0, s[12:13]
	global_load_dwordx4 v[120:123], v0, s[12:13] offset:16
	s_add_u32 s12, s12, 0x400000
	s_addc_u32 s13, s13, 0
	global_load_dwordx4 v[124:127], v0, s[12:13]
	global_load_dwordx4 v[128:131], v0, s[12:13] offset:16
	s_add_u32 s12, s12, 0x400000
	s_addc_u32 s13, s13, 0
	global_load_dwordx4 v[132:135], v0, s[12:13]
	global_load_dwordx4 v[136:139], v0, s[12:13] offset:16
	s_add_u32 s12, s12, 0x400000
	s_addc_u32 s13, s13, 0
	global_load_dwordx4 v[140:143], v0, s[12:13]
	global_load_dwordx4 v[144:147], v0, s[12:13] offset:16
	s_waitcnt vmcnt(16)
	s_nop 1
	v_cvt_pk_bf16_f32 v180, v20, v21
	v_cvt_pk_bf16_f32 v181, v22, v23
	v_cvt_pk_bf16_f32 v182, v24, v25
	v_cvt_pk_bf16_f32 v183, v26, v27
	v_cvt_pk_bf16_f32 v184, v28, v29
	v_cvt_pk_bf16_f32 v185, v30, v31
	v_cvt_pk_bf16_f32 v186, v32, v33
	v_cvt_pk_bf16_f32 v187, v34, v35
	v_cvt_pk_bf16_f32 v188, v36, v37
	v_cvt_pk_bf16_f32 v189, v38, v39
	v_cvt_pk_bf16_f32 v190, v40, v41
	v_cvt_pk_bf16_f32 v191, v42, v43
	v_cvt_pk_bf16_f32 v192, v44, v45
	v_cvt_pk_bf16_f32 v193, v46, v47
	v_cvt_pk_bf16_f32 v194, v48, v49
	v_cvt_pk_bf16_f32 v195, v50, v51
	v_cvt_pk_bf16_f32 v196, v52, v53
	v_cvt_pk_bf16_f32 v197, v54, v55
	v_cvt_pk_bf16_f32 v198, v56, v57
	v_cvt_pk_bf16_f32 v199, v58, v59
	v_cvt_pk_bf16_f32 v200, v60, v61
	v_cvt_pk_bf16_f32 v201, v62, v63
	v_cvt_pk_bf16_f32 v202, v64, v65
	v_cvt_pk_bf16_f32 v203, v66, v67
	v_cvt_pk_bf16_f32 v204, v68, v69
	v_cvt_pk_bf16_f32 v205, v70, v71
	v_cvt_pk_bf16_f32 v206, v72, v73
	v_cvt_pk_bf16_f32 v207, v74, v75
	v_cvt_pk_bf16_f32 v208, v76, v77
	v_cvt_pk_bf16_f32 v209, v78, v79
	v_cvt_pk_bf16_f32 v210, v80, v81
	v_cvt_pk_bf16_f32 v211, v82, v83
	global_store_dwordx4 v2, v[180:183], s[16:17]
	s_add_u32 s16, s16, 0x200000
	s_addc_u32 s17, s17, 0
	global_store_dwordx4 v2, v[184:187], s[16:17]
	s_add_u32 s16, s16, 0x200000
	s_addc_u32 s17, s17, 0
	global_store_dwordx4 v2, v[188:191], s[16:17]
	s_add_u32 s16, s16, 0x200000
	s_addc_u32 s17, s17, 0
	global_store_dwordx4 v2, v[192:195], s[16:17]
	s_add_u32 s16, s16, 0x200000
	s_addc_u32 s17, s17, 0
	global_store_dwordx4 v2, v[196:199], s[16:17]
	s_add_u32 s16, s16, 0x200000
	s_addc_u32 s17, s17, 0
	global_store_dwordx4 v2, v[200:203], s[16:17]
	s_add_u32 s16, s16, 0x200000
	s_addc_u32 s17, s17, 0
	global_store_dwordx4 v2, v[204:207], s[16:17]
	s_add_u32 s16, s16, 0x200000
	s_addc_u32 s17, s17, 0
	global_store_dwordx4 v2, v[208:211], s[16:17]
	s_add_u32 s16, s16, 0x200000
	s_addc_u32 s17, s17, 0
	s_waitcnt vmcnt(8)
	s_nop 1
	v_cvt_pk_bf16_f32 v180, v84, v85
	v_cvt_pk_bf16_f32 v181, v86, v87
	v_cvt_pk_bf16_f32 v182, v88, v89
	v_cvt_pk_bf16_f32 v183, v90, v91
	v_cvt_pk_bf16_f32 v184, v92, v93
	v_cvt_pk_bf16_f32 v185, v94, v95
	v_cvt_pk_bf16_f32 v186, v96, v97
	v_cvt_pk_bf16_f32 v187, v98, v99
	v_cvt_pk_bf16_f32 v188, v100, v101
	v_cvt_pk_bf16_f32 v189, v102, v103
	v_cvt_pk_bf16_f32 v190, v104, v105
	v_cvt_pk_bf16_f32 v191, v106, v107
	v_cvt_pk_bf16_f32 v192, v108, v109
	v_cvt_pk_bf16_f32 v193, v110, v111
	v_cvt_pk_bf16_f32 v194, v112, v113
	v_cvt_pk_bf16_f32 v195, v114, v115
	v_cvt_pk_bf16_f32 v196, v116, v117
	v_cvt_pk_bf16_f32 v197, v118, v119
	v_cvt_pk_bf16_f32 v198, v120, v121
	v_cvt_pk_bf16_f32 v199, v122, v123
	v_cvt_pk_bf16_f32 v200, v124, v125
	v_cvt_pk_bf16_f32 v201, v126, v127
	v_cvt_pk_bf16_f32 v202, v128, v129
	v_cvt_pk_bf16_f32 v203, v130, v131
	v_cvt_pk_bf16_f32 v204, v132, v133
	v_cvt_pk_bf16_f32 v205, v134, v135
	v_cvt_pk_bf16_f32 v206, v136, v137
	v_cvt_pk_bf16_f32 v207, v138, v139
	v_cvt_pk_bf16_f32 v208, v140, v141
	v_cvt_pk_bf16_f32 v209, v142, v143
	v_cvt_pk_bf16_f32 v210, v144, v145
	v_cvt_pk_bf16_f32 v211, v146, v147
	global_store_dwordx4 v2, v[180:183], s[16:17]
	s_add_u32 s16, s16, 0x200000
	s_addc_u32 s17, s17, 0
	global_store_dwordx4 v2, v[184:187], s[16:17]
	s_add_u32 s16, s16, 0x200000
	s_addc_u32 s17, s17, 0
	global_store_dwordx4 v2, v[188:191], s[16:17]
	s_add_u32 s16, s16, 0x200000
	s_addc_u32 s17, s17, 0
	global_store_dwordx4 v2, v[192:195], s[16:17]
	s_add_u32 s16, s16, 0x200000
	s_addc_u32 s17, s17, 0
	global_store_dwordx4 v2, v[196:199], s[16:17]
	s_add_u32 s16, s16, 0x200000
	s_addc_u32 s17, s17, 0
	global_store_dwordx4 v2, v[200:203], s[16:17]
	s_add_u32 s16, s16, 0x200000
	s_addc_u32 s17, s17, 0
	global_store_dwordx4 v2, v[204:207], s[16:17]
	s_add_u32 s16, s16, 0x200000
	s_addc_u32 s17, s17, 0
	global_store_dwordx4 v2, v[208:211], s[16:17]
	s_add_u32 s16, s16, 0x200000
	s_addc_u32 s17, s17, 0
	s_mov_b64 s[14:15], 0
	v_cmp_gt_i64_e32 vcc, s[14:15], v[4:5]
	s_and_saveexec_b64 s[16:17], vcc
	s_cbranch_execz .LBB0_112
	s_add_u32 s18, s80, 0x1a00000
	s_addc_u32 s19, s81, 0
	s_lshl_b64 s[0:1], s[74:75], 12
	s_lshl_b64 s[6:7], s[60:61], 12
	v_readlane_b32 s44, v234, 2
	s_add_u32 s6, s0, s6
	v_lshlrev_b64 v[0:1], 4, v[6:7]
	v_readlane_b32 s45, v234, 3
	s_addc_u32 s7, s1, s7
	s_lshl_b64 s[20:21], s[60:61], 14
	s_waitcnt vmcnt(13)
	v_lshl_add_u64 v[26:27], s[0:1], 0, v[0:1]
	s_lshl_b64 s[0:1], s[74:75], 13
	s_mov_b64 s[36:37], s[44:45]
	s_add_u32 s0, s36, s0
	v_lshl_add_u64 v[24:25], s[6:7], 0, v[0:1]
	v_lshlrev_b64 v[0:1], 5, v[6:7]
	s_addc_u32 s1, s37, s1
	s_lshl_b64 s[22:23], s[60:61], 15
	s_lshl_b64 s[24:25], s[60:61], 9
	v_lshl_add_u64 v[0:1], s[0:1], 0, v[0:1]
	s_add_u32 s0, s24, s10
	s_addc_u32 s1, s25, s11
	s_mul_i32 s26, s60, 0x300
	s_waitcnt vmcnt(11)
	v_lshl_add_u64 v[28:29], v[0:1], 0, 16
	v_lshl_add_u64 v[0:1], s[0:1], 0, v[6:7]
	s_mul_hi_u32 s27, s60, 0x300
	s_add_u32 s0, s26, s10
	s_addc_u32 s1, s27, s11
	s_waitcnt vmcnt(9)
	v_lshlrev_b64 v[30:31], 4, v[0:1]
	v_lshl_add_u64 v[0:1], s[0:1], 0, v[6:7]
	v_lshlrev_b64 v[32:33], 4, v[0:1]
	s_mov_b64 s[10:11], 0
	s_mov_b64 s[28:29], 0x1fffff
	v_readlane_b32 s46, v234, 4
	v_readlane_b32 s47, v234, 5
	v_readlane_b32 s48, v234, 6
	v_readlane_b32 s49, v234, 7
	v_readlane_b32 s50, v234, 8
	v_readlane_b32 s51, v234, 9
	v_readlane_b32 s52, v234, 10
	v_readlane_b32 s53, v234, 11
	v_readlane_b32 s54, v234, 12
	v_readlane_b32 s55, v234, 13
	v_readlane_b32 s56, v234, 14
	v_readlane_b32 s57, v234, 15
	v_readlane_b32 s58, v234, 16
	v_readlane_b32 s59, v234, 17
	s_branch .LBB0_106
